# exact in-order vmcnt counts (stores counted) in the hoisted P3-final and P6 epilogues instead of loads-only counts; same layout as v37
# baseline (speedup 1.0000x reference)
; __device__ __forceinline__ float bf_lo(unsigned w) { return __uint_as_float(w << 16); }
; __device__ __forceinline__ float bf_hi(unsigned w) { return __uint_as_float(w & 0xffff0000u); }
; __device__ __forceinline__ float sigm(float x) { return __builtin_amdgcn_rcpf(1.0f + __builtin_amdgcn_exp2f(-1.4426950408889634f * x)); }
; __device__ __forceinline__ u32x4 pack8(f32x4 a, f32x4 b) { u32x4 w; w.x = cvt_pk_bf16(a[0], a[1]); w.y = cvt_pk_bf16(a[2], a[3]); w.z = cvt_pk_bf16(b[0], b[1]); w.w = cvt_pk_bf16(b[2], b[3]); return w; }
;     __device__ __forceinline__ void operator()(const f32x4 (&acc)[2][2][4][2], const Unit& u, int wr, int wc, int fr, int fq) const {
;         const int row0 = u.pm * BM + wr * 64 + fr, col0 = u.pn * BM + wc * 32 + 8 * fq;
; #pragma unroll
;         for (int ai = 0; ai < 2; ++ai)
; #pragma unroll
;             for (int m = 0; m < 4; ++m) { const size_t ro = (size_t)(row0 + ai * HALF + m * 16) * 1024 + col0;
; #pragma unroll
;                 for (int bj = 0; bj < 2; ++bj) { const size_t o = ro + bj * HALF; const u32x4 b = *(const u32x4*)(GBr + o);
;                     f32x4 s0, s1; s0[0] = sigm(fmaxf(bf_lo(b.x), -30.f)); s0[1] = sigm(fmaxf(bf_hi(b.x), -30.f)); s0[2] = sigm(fmaxf(bf_lo(b.y), -30.f)); s0[3] = sigm(fmaxf(bf_hi(b.y), -30.f));
;                     s1[0] = sigm(fmaxf(bf_lo(b.z), -30.f)); s1[1] = sigm(fmaxf(bf_hi(b.z), -30.f)); s1[2] = sigm(fmaxf(bf_lo(b.w), -30.f)); s1[3] = sigm(fmaxf(bf_hi(b.w), -30.f));
;                     *(u32x4*)(Mx + o) = pack8(s0 * acc[ai][bj][m][0], s1 * acc[ai][bj][m][1]); } }
.LBB0_1032:
	v_lshl_add_u32 v2, s56, 8, v179
	v_ashrrev_i32_e32 v3, 31, v2
	v_lshl_or_b32 v168, s0, 8, v181
	v_lshlrev_b64 v[132:133], 10, v[2:3]
	v_ashrrev_i32_e32 v169, 31, v168
	s_cmp_lg_u32 s1, 0
	v_lshl_add_u64 v[132:133], v[132:133], 0, v[168:169]
	s_cselect_b64 s[54:55], -1, 0
	v_lshlrev_b64 v[142:143], 1, v[132:133]
	v_or_b32_e32 v172, 16, v2
	v_or_b32_e32 v170, 32, v2
	s_and_b64 vcc, exec, s[54:55]
	v_lshl_add_u64 v[132:133], s[6:7], 0, v[142:143]
	v_or_b32_e32 v140, 0x100, v142
	v_ashrrev_i32_e32 v173, 31, v172
	v_ashrrev_i32_e32 v171, 31, v170
	s_cbranch_vccz .LBB0_1040
	v_mov_b32_e32 v228, v132
	v_mov_b32_e32 v229, v133
	s_mov_b32 s98, 0x8000
	s_mov_b32 s99, 0
	global_load_dwordx4 v[184:187], v[228:229], off
	global_load_dwordx4 v[188:191], v[228:229], off offset:256
	v_lshl_add_u64 v[228:229], v[228:229], 0, s[98:99]
	global_load_dwordx4 v[192:195], v[228:229], off
	global_load_dwordx4 v[196:199], v[228:229], off offset:256
	v_lshl_add_u64 v[228:229], v[228:229], 0, s[98:99]
	global_load_dwordx4 v[200:203], v[228:229], off
	global_load_dwordx4 v[204:207], v[228:229], off offset:256
	v_lshl_add_u64 v[228:229], v[228:229], 0, s[98:99]
	global_load_dwordx4 v[208:211], v[228:229], off
	global_load_dwordx4 v[212:215], v[228:229], off offset:256
	v_lshl_add_u64 v[228:229], v[228:229], 0, s[98:99]
	v_lshl_add_u64 v[228:229], v[228:229], 0, s[98:99]
	v_lshl_add_u64 v[228:229], v[228:229], 0, s[98:99]
	v_lshl_add_u64 v[228:229], v[228:229], 0, s[98:99]
	v_lshl_add_u64 v[228:229], v[228:229], 0, s[98:99]
	global_load_dwordx4 v[216:219], v[228:229], off
	global_load_dwordx4 v[220:223], v[228:229], off offset:256
	v_lshl_add_u64 v[228:229], v[228:229], 0, s[98:99]
	global_load_dwordx4 v[224:227], v[228:229], off
	global_load_dwordx4 v[238:241], v[228:229], off offset:256
	v_lshl_add_u64 v[228:229], v[228:229], 0, s[98:99]
	global_load_dwordx4 v[242:245], v[228:229], off
	global_load_dwordx4 v[246:249], v[228:229], off offset:256
	v_lshl_add_u64 v[228:229], v[228:229], 0, s[98:99]
	global_load_dwordx4 v[252:255], v[228:229], off
	s_nop 1
	v_lshl_add_u64 v[138:139], s[16:17], 0, v[142:143]
	v_mov_b32_e32 v141, v143
	v_lshl_add_u64 v[144:145], s[6:7], 0, v[140:141]
	s_waitcnt vmcnt(14)
	v_lshlrev_b32_e32 v1, 16, v184
	v_and_b32_e32 v134, 0xffff0000, v184
	v_lshlrev_b32_e32 v146, 16, v185
	v_and_b32_e32 v135, 0xffff0000, v185
	v_lshlrev_b32_e32 v147, 16, v186
	v_and_b32_e32 v136, 0xffff0000, v186
	v_lshlrev_b32_e32 v148, 16, v187
	v_and_b32_e32 v137, 0xffff0000, v187
	global_load_dwordx4 v[184:187], v[228:229], off offset:256
	v_max_f32_e32 v1, v1, v1
	v_max_f32_e32 v134, v134, v134
	v_max_f32_e32 v146, v146, v146
	v_max_f32_e32 v135, v135, v135
	v_max_f32_e32 v147, v147, v147
	v_max_f32_e32 v136, v136, v136
	v_max_f32_e32 v148, v148, v148
	v_max_f32_e32 v137, v137, v137
	v_max_f32_e32 v1, 0xc1f00000, v1
	v_max_f32_e32 v134, 0xc1f00000, v134
	v_max_f32_e32 v146, 0xc1f00000, v146
	v_max_f32_e32 v135, 0xc1f00000, v135
	v_max_f32_e32 v147, 0xc1f00000, v147
	v_max_f32_e32 v136, 0xc1f00000, v136
	v_max_f32_e32 v148, 0xc1f00000, v148
	v_max_f32_e32 v137, 0xc1f00000, v137
	v_mul_f32_e32 v1, 0xbfb8aa3b, v1
	v_mul_f32_e32 v134, 0xbfb8aa3b, v134
	v_mul_f32_e32 v146, 0xbfb8aa3b, v146
	v_mul_f32_e32 v135, 0xbfb8aa3b, v135
	v_mul_f32_e32 v147, 0xbfb8aa3b, v147
	v_mul_f32_e32 v136, 0xbfb8aa3b, v136
	v_mul_f32_e32 v148, 0xbfb8aa3b, v148
	v_mul_f32_e32 v137, 0xbfb8aa3b, v137
	v_exp_f32_e32 v1, v1
	v_exp_f32_e32 v134, v134
	v_exp_f32_e32 v146, v146
	v_exp_f32_e32 v135, v135
	v_exp_f32_e32 v147, v147
	v_exp_f32_e32 v136, v136
	v_exp_f32_e32 v148, v148
	v_exp_f32_e32 v137, v137
	v_add_f32_e32 v1, 1.0, v1
	v_add_f32_e32 v149, 1.0, v134
	v_add_f32_e32 v146, 1.0, v146
	v_add_f32_e32 v150, 1.0, v135
	v_add_f32_e32 v147, 1.0, v147
	v_add_f32_e32 v151, 1.0, v136
	v_add_f32_e32 v148, 1.0, v148
	v_add_f32_e32 v174, 1.0, v137
	v_rcp_f32_e32 v134, v1
	v_rcp_f32_e32 v135, v149
	v_rcp_f32_e32 v136, v146
	v_rcp_f32_e32 v137, v150
	v_rcp_f32_e32 v146, v147
	v_rcp_f32_e32 v148, v148
	v_rcp_f32_e32 v149, v174
	v_rcp_f32_e32 v147, v151
	v_pk_mul_f32 v[136:137], v[130:131], v[136:137]
	v_pk_mul_f32 v[134:135], v[128:129], v[134:135]
	v_pk_mul_f32 v[148:149], v[126:127], v[148:149]
	v_pk_mul_f32 v[146:147], v[124:125], v[146:147]
	v_cvt_pk_bf16_f32 v134, v134, v135
	v_cvt_pk_bf16_f32 v135, v136, v137
	s_nop 0
	v_cvt_pk_bf16_f32 v136, v146, v147
	v_cvt_pk_bf16_f32 v137, v148, v149
	global_store_dwordx4 v[138:139], v[134:137], off
	s_nop 1
	v_lshl_add_u64 v[138:139], s[16:17], 0, v[140:141]
	v_lshlrev_b64 v[134:135], 10, v[172:173]
	v_lshl_add_u64 v[134:135], v[134:135], 0, v[168:169]
	v_lshlrev_b64 v[136:137], 1, v[134:135]
	v_lshl_add_u64 v[134:135], s[6:7], 0, v[136:137]
	s_waitcnt vmcnt(15)
; __device__ __forceinline__ float bf_lo(unsigned w) { return __uint_as_float(w << 16); }
; __device__ __forceinline__ float bf_hi(unsigned w) { return __uint_as_float(w & 0xffff0000u); }
; __device__ __forceinline__ float sigm(float x) { return __builtin_amdgcn_rcpf(1.0f + __builtin_amdgcn_exp2f(-1.4426950408889634f * x)); }
; __device__ __forceinline__ u32x4 pack8(f32x4 a, f32x4 b) { u32x4 w; w.x = cvt_pk_bf16(a[0], a[1]); w.y = cvt_pk_bf16(a[2], a[3]); w.z = cvt_pk_bf16(b[0], b[1]); w.w = cvt_pk_bf16(b[2], b[3]); return w; }
;     __device__ __forceinline__ void operator()(const f32x4 (&acc)[2][2][4][2], const Unit& u, int wr, int wc, int fr, int fq) const {
;     ...
;                 for (int bj = 0; bj < 2; ++bj) { const size_t o = ro + bj * HALF; const u32x4 b = *(const u32x4*)(GBr + o);
;                     f32x4 s0, s1; s0[0] = sigm(fmaxf(bf_lo(b.x), -30.f)); s0[1] = sigm(fmaxf(bf_hi(b.x), -30.f)); s0[2] = sigm(fmaxf(bf_lo(b.y), -30.f)); s0[3] = sigm(fmaxf(bf_hi(b.y), -30.f));
;                     s1[0] = sigm(fmaxf(bf_lo(b.z), -30.f)); s1[1] = sigm(fmaxf(bf_hi(b.z), -30.f)); s1[2] = sigm(fmaxf(bf_lo(b.w), -30.f)); s1[3] = sigm(fmaxf(bf_hi(b.w), -30.f));
;                     *(u32x4*)(Mx + o) = pack8(s0 * acc[ai][bj][m][0], s1 * acc[ai][bj][m][1]); } }
	v_lshlrev_b32_e32 v1, 16, v188
	v_and_b32_e32 v141, 0xffff0000, v188
	v_lshlrev_b32_e32 v144, 16, v189
	v_and_b32_e32 v145, 0xffff0000, v189
	v_lshlrev_b32_e32 v148, 16, v190
	v_and_b32_e32 v146, 0xffff0000, v190
	v_lshlrev_b32_e32 v149, 16, v191
	v_and_b32_e32 v147, 0xffff0000, v191
	v_max_f32_e32 v1, v1, v1
	v_max_f32_e32 v141, v141, v141
	v_max_f32_e32 v144, v144, v144
	v_max_f32_e32 v145, v145, v145
	v_max_f32_e32 v148, v148, v148
	v_max_f32_e32 v146, v146, v146
	v_max_f32_e32 v149, v149, v149
	v_max_f32_e32 v147, v147, v147
	v_max_f32_e32 v1, 0xc1f00000, v1
	v_max_f32_e32 v141, 0xc1f00000, v141
	v_max_f32_e32 v144, 0xc1f00000, v144
	v_max_f32_e32 v145, 0xc1f00000, v145
	v_max_f32_e32 v148, 0xc1f00000, v148
	v_max_f32_e32 v146, 0xc1f00000, v146
	v_max_f32_e32 v149, 0xc1f00000, v149
	v_max_f32_e32 v147, 0xc1f00000, v147
	v_mul_f32_e32 v1, 0xbfb8aa3b, v1
	v_mul_f32_e32 v141, 0xbfb8aa3b, v141
	v_mul_f32_e32 v144, 0xbfb8aa3b, v144
	v_mul_f32_e32 v145, 0xbfb8aa3b, v145
	v_mul_f32_e32 v148, 0xbfb8aa3b, v148
	v_mul_f32_e32 v146, 0xbfb8aa3b, v146
	v_mul_f32_e32 v149, 0xbfb8aa3b, v149
	v_mul_f32_e32 v147, 0xbfb8aa3b, v147
	v_exp_f32_e32 v1, v1
	v_exp_f32_e32 v141, v141
	v_exp_f32_e32 v144, v144
	v_exp_f32_e32 v145, v145
	v_exp_f32_e32 v148, v148
	v_exp_f32_e32 v146, v146
	v_exp_f32_e32 v149, v149
	v_exp_f32_e32 v147, v147
	v_add_f32_e32 v1, 1.0, v1
	v_add_f32_e32 v141, 1.0, v141
	v_add_f32_e32 v150, 1.0, v144
	v_add_f32_e32 v151, 1.0, v145
	v_add_f32_e32 v148, 1.0, v148
	v_add_f32_e32 v174, 1.0, v146
	v_add_f32_e32 v149, 1.0, v149
	v_add_f32_e32 v175, 1.0, v147
	v_rcp_f32_e32 v144, v1
	v_rcp_f32_e32 v145, v141
	v_rcp_f32_e32 v146, v150
	v_rcp_f32_e32 v147, v151
	v_rcp_f32_e32 v148, v148
	v_rcp_f32_e32 v150, v149
	v_rcp_f32_e32 v151, v175
	v_rcp_f32_e32 v149, v174
	v_pk_mul_f32 v[146:147], v[98:99], v[146:147]
	v_pk_mul_f32 v[144:145], v[96:97], v[144:145]
	v_pk_mul_f32 v[150:151], v[94:95], v[150:151]
	v_pk_mul_f32 v[148:149], v[92:93], v[148:149]
	v_cvt_pk_bf16_f32 v144, v144, v145
	v_cvt_pk_bf16_f32 v145, v146, v147
	s_nop 0
	v_cvt_pk_bf16_f32 v146, v148, v149
	v_cvt_pk_bf16_f32 v147, v150, v151
	global_store_dwordx4 v[138:139], v[144:147], off
	s_nop 1
	v_lshl_add_u64 v[134:135], s[16:17], 0, v[136:137]
	v_or_b32_e32 v136, 0x100, v136
	v_lshl_add_u64 v[138:139], s[6:7], 0, v[136:137]
	s_waitcnt vmcnt(15)
	v_lshlrev_b32_e32 v1, 16, v192
	v_and_b32_e32 v141, 0xffff0000, v192
	v_lshlrev_b32_e32 v144, 16, v193
	v_and_b32_e32 v145, 0xffff0000, v193
	v_lshlrev_b32_e32 v148, 16, v194
	v_and_b32_e32 v146, 0xffff0000, v194
	v_lshlrev_b32_e32 v149, 16, v195
	v_and_b32_e32 v147, 0xffff0000, v195
	v_max_f32_e32 v1, v1, v1
	v_max_f32_e32 v141, v141, v141
	v_max_f32_e32 v144, v144, v144
	v_max_f32_e32 v145, v145, v145
	v_max_f32_e32 v148, v148, v148
	v_max_f32_e32 v146, v146, v146
	v_max_f32_e32 v149, v149, v149
	v_max_f32_e32 v147, v147, v147
	v_max_f32_e32 v1, 0xc1f00000, v1
	v_max_f32_e32 v141, 0xc1f00000, v141
	v_max_f32_e32 v144, 0xc1f00000, v144
	v_max_f32_e32 v145, 0xc1f00000, v145
	v_max_f32_e32 v148, 0xc1f00000, v148
	v_max_f32_e32 v146, 0xc1f00000, v146
	v_max_f32_e32 v149, 0xc1f00000, v149
	v_max_f32_e32 v147, 0xc1f00000, v147
	v_mul_f32_e32 v1, 0xbfb8aa3b, v1
	v_mul_f32_e32 v141, 0xbfb8aa3b, v141
	v_mul_f32_e32 v144, 0xbfb8aa3b, v144
	v_mul_f32_e32 v145, 0xbfb8aa3b, v145
	v_mul_f32_e32 v148, 0xbfb8aa3b, v148
	v_mul_f32_e32 v146, 0xbfb8aa3b, v146
	v_mul_f32_e32 v149, 0xbfb8aa3b, v149
	v_mul_f32_e32 v147, 0xbfb8aa3b, v147
	v_exp_f32_e32 v1, v1
	v_exp_f32_e32 v141, v141
	v_exp_f32_e32 v144, v144
	v_exp_f32_e32 v145, v145
	v_exp_f32_e32 v148, v148
	v_exp_f32_e32 v146, v146
	v_exp_f32_e32 v149, v149
	v_exp_f32_e32 v147, v147
	v_add_f32_e32 v1, 1.0, v1
	v_add_f32_e32 v141, 1.0, v141
	v_add_f32_e32 v150, 1.0, v144
	v_add_f32_e32 v151, 1.0, v145
	v_add_f32_e32 v148, 1.0, v148
	v_add_f32_e32 v174, 1.0, v146
	v_add_f32_e32 v149, 1.0, v149
	v_add_f32_e32 v175, 1.0, v147
	v_rcp_f32_e32 v144, v1
	v_rcp_f32_e32 v145, v141
	v_rcp_f32_e32 v146, v150
	v_rcp_f32_e32 v147, v151
	v_rcp_f32_e32 v148, v148
	v_rcp_f32_e32 v150, v149
	v_rcp_f32_e32 v151, v175
	v_rcp_f32_e32 v149, v174
	v_pk_mul_f32 v[146:147], v[122:123], v[146:147]
	v_pk_mul_f32 v[144:145], v[120:121], v[144:145]
	v_pk_mul_f32 v[150:151], v[118:119], v[150:151]
	v_pk_mul_f32 v[148:149], v[116:117], v[148:149]
	v_cvt_pk_bf16_f32 v144, v144, v145
	v_cvt_pk_bf16_f32 v145, v146, v147
	s_nop 0
	v_cvt_pk_bf16_f32 v146, v148, v149
	v_cvt_pk_bf16_f32 v147, v150, v151
	global_store_dwordx4 v[134:135], v[144:147], off
	s_nop 1
	v_lshl_add_u64 v[150:151], s[16:17], 0, v[136:137]
	v_lshlrev_b64 v[134:135], 10, v[170:171]
	v_lshl_add_u64 v[134:135], v[134:135], 0, v[168:169]
	v_lshlrev_b64 v[134:135], 1, v[134:135]
	v_lshl_add_u64 v[148:149], s[6:7], 0, v[134:135]
	s_waitcnt vmcnt(15)
; __device__ __forceinline__ float bf_lo(unsigned w) { return __uint_as_float(w << 16); }
; __device__ __forceinline__ float bf_hi(unsigned w) { return __uint_as_float(w & 0xffff0000u); }
; __device__ __forceinline__ float sigm(float x) { return __builtin_amdgcn_rcpf(1.0f + __builtin_amdgcn_exp2f(-1.4426950408889634f * x)); }
; __device__ __forceinline__ u32x4 pack8(f32x4 a, f32x4 b) { u32x4 w; w.x = cvt_pk_bf16(a[0], a[1]); w.y = cvt_pk_bf16(a[2], a[3]); w.z = cvt_pk_bf16(b[0], b[1]); w.w = cvt_pk_bf16(b[2], b[3]); return w; }
;     __device__ __forceinline__ void operator()(const f32x4 (&acc)[2][2][4][2], const Unit& u, int wr, int wc, int fr, int fq) const {
;     ...
;                 for (int bj = 0; bj < 2; ++bj) { const size_t o = ro + bj * HALF; const u32x4 b = *(const u32x4*)(GBr + o);
;                     f32x4 s0, s1; s0[0] = sigm(fmaxf(bf_lo(b.x), -30.f)); s0[1] = sigm(fmaxf(bf_hi(b.x), -30.f)); s0[2] = sigm(fmaxf(bf_lo(b.y), -30.f)); s0[3] = sigm(fmaxf(bf_hi(b.y), -30.f));
;                     s1[0] = sigm(fmaxf(bf_lo(b.z), -30.f)); s1[1] = sigm(fmaxf(bf_hi(b.z), -30.f)); s1[2] = sigm(fmaxf(bf_lo(b.w), -30.f)); s1[3] = sigm(fmaxf(bf_hi(b.w), -30.f));
;                     *(u32x4*)(Mx + o) = pack8(s0 * acc[ai][bj][m][0], s1 * acc[ai][bj][m][1]); } }
	v_lshlrev_b32_e32 v1, 16, v196
	v_and_b32_e32 v136, 0xffff0000, v196
	v_lshlrev_b32_e32 v137, 16, v197
	v_and_b32_e32 v138, 0xffff0000, v197
	v_lshlrev_b32_e32 v139, 16, v198
	v_and_b32_e32 v141, 0xffff0000, v198
	v_lshlrev_b32_e32 v144, 16, v199
	v_and_b32_e32 v145, 0xffff0000, v199
	v_max_f32_e32 v1, v1, v1
	v_max_f32_e32 v136, v136, v136
	v_max_f32_e32 v137, v137, v137
	v_max_f32_e32 v138, v138, v138
	v_max_f32_e32 v139, v139, v139
	v_max_f32_e32 v141, v141, v141
	v_max_f32_e32 v144, v144, v144
	v_max_f32_e32 v145, v145, v145
	v_max_f32_e32 v1, 0xc1f00000, v1
	v_max_f32_e32 v136, 0xc1f00000, v136
	v_max_f32_e32 v137, 0xc1f00000, v137
	v_max_f32_e32 v138, 0xc1f00000, v138
	v_max_f32_e32 v139, 0xc1f00000, v139
	v_max_f32_e32 v141, 0xc1f00000, v141
	v_max_f32_e32 v144, 0xc1f00000, v144
	v_max_f32_e32 v145, 0xc1f00000, v145
	v_mul_f32_e32 v1, 0xbfb8aa3b, v1
	v_mul_f32_e32 v136, 0xbfb8aa3b, v136
	v_mul_f32_e32 v137, 0xbfb8aa3b, v137
	v_mul_f32_e32 v138, 0xbfb8aa3b, v138
	v_mul_f32_e32 v139, 0xbfb8aa3b, v139
	v_mul_f32_e32 v141, 0xbfb8aa3b, v141
	v_mul_f32_e32 v144, 0xbfb8aa3b, v144
	v_mul_f32_e32 v145, 0xbfb8aa3b, v145
	v_exp_f32_e32 v1, v1
	v_exp_f32_e32 v136, v136
	v_exp_f32_e32 v137, v137
	v_exp_f32_e32 v138, v138
	v_exp_f32_e32 v139, v139
	v_exp_f32_e32 v141, v141
	v_exp_f32_e32 v144, v144
	v_exp_f32_e32 v145, v145
	v_add_f32_e32 v1, 1.0, v1
	v_add_f32_e32 v146, 1.0, v136
	v_add_f32_e32 v147, 1.0, v137
	v_add_f32_e32 v174, 1.0, v138
	v_add_f32_e32 v175, 1.0, v139
	v_add_f32_e32 v141, 1.0, v141
	v_add_f32_e32 v176, 1.0, v144
	v_add_f32_e32 v145, 1.0, v145
	v_rcp_f32_e32 v136, v1
	v_rcp_f32_e32 v137, v146
	v_rcp_f32_e32 v138, v147
	v_rcp_f32_e32 v139, v174
	v_rcp_f32_e32 v144, v175
	v_rcp_f32_e32 v146, v176
	v_rcp_f32_e32 v147, v145
	v_rcp_f32_e32 v145, v141
	v_pk_mul_f32 v[138:139], v[90:91], v[138:139]
	v_pk_mul_f32 v[136:137], v[88:89], v[136:137]
	v_pk_mul_f32 v[146:147], v[86:87], v[146:147]
	v_pk_mul_f32 v[144:145], v[84:85], v[144:145]
	v_cvt_pk_bf16_f32 v136, v136, v137
	v_cvt_pk_bf16_f32 v137, v138, v139
	s_nop 0
	v_cvt_pk_bf16_f32 v138, v144, v145
	v_cvt_pk_bf16_f32 v139, v146, v147
	global_store_dwordx4 v[150:151], v[136:139], off
	s_nop 1
	v_lshl_add_u64 v[144:145], s[16:17], 0, v[134:135]
	v_or_b32_e32 v134, 0x100, v134
	v_lshl_add_u64 v[146:147], s[6:7], 0, v[134:135]
	s_waitcnt vmcnt(15)
	v_lshlrev_b32_e32 v1, 16, v200
	v_and_b32_e32 v136, 0xffff0000, v200
	v_lshlrev_b32_e32 v141, 16, v201
	v_and_b32_e32 v137, 0xffff0000, v201
	v_lshlrev_b32_e32 v148, 16, v202
	v_and_b32_e32 v138, 0xffff0000, v202
	v_lshlrev_b32_e32 v149, 16, v203
	v_and_b32_e32 v139, 0xffff0000, v203
	v_max_f32_e32 v1, v1, v1
	v_max_f32_e32 v136, v136, v136
	v_max_f32_e32 v141, v141, v141
	v_max_f32_e32 v137, v137, v137
	v_max_f32_e32 v148, v148, v148
	v_max_f32_e32 v138, v138, v138
	v_max_f32_e32 v149, v149, v149
	v_max_f32_e32 v139, v139, v139
	v_max_f32_e32 v1, 0xc1f00000, v1
	v_max_f32_e32 v136, 0xc1f00000, v136
	v_max_f32_e32 v141, 0xc1f00000, v141
	v_max_f32_e32 v137, 0xc1f00000, v137
	v_max_f32_e32 v148, 0xc1f00000, v148
	v_max_f32_e32 v138, 0xc1f00000, v138
	v_max_f32_e32 v149, 0xc1f00000, v149
	v_max_f32_e32 v139, 0xc1f00000, v139
	v_mul_f32_e32 v1, 0xbfb8aa3b, v1
	v_mul_f32_e32 v136, 0xbfb8aa3b, v136
	v_mul_f32_e32 v141, 0xbfb8aa3b, v141
	v_mul_f32_e32 v137, 0xbfb8aa3b, v137
	v_mul_f32_e32 v148, 0xbfb8aa3b, v148
	v_mul_f32_e32 v138, 0xbfb8aa3b, v138
	v_mul_f32_e32 v149, 0xbfb8aa3b, v149
	v_mul_f32_e32 v139, 0xbfb8aa3b, v139
	v_exp_f32_e32 v1, v1
	v_exp_f32_e32 v136, v136
	v_exp_f32_e32 v141, v141
	v_exp_f32_e32 v137, v137
	v_exp_f32_e32 v148, v148
	v_exp_f32_e32 v138, v138
	v_exp_f32_e32 v149, v149
	v_exp_f32_e32 v139, v139
	v_add_f32_e32 v1, 1.0, v1
	v_add_f32_e32 v150, 1.0, v136
	v_add_f32_e32 v141, 1.0, v141
	v_add_f32_e32 v151, 1.0, v137
	v_add_f32_e32 v148, 1.0, v148
	v_add_f32_e32 v174, 1.0, v138
	v_add_f32_e32 v149, 1.0, v149
	v_add_f32_e32 v175, 1.0, v139
	v_rcp_f32_e32 v136, v1
	v_rcp_f32_e32 v137, v150
	v_rcp_f32_e32 v138, v141
	v_rcp_f32_e32 v139, v151
	v_rcp_f32_e32 v148, v148
	v_rcp_f32_e32 v150, v149
	v_rcp_f32_e32 v151, v175
	v_rcp_f32_e32 v149, v174
	v_pk_mul_f32 v[138:139], v[114:115], v[138:139]
	v_pk_mul_f32 v[136:137], v[112:113], v[136:137]
	v_pk_mul_f32 v[150:151], v[110:111], v[150:151]
	v_pk_mul_f32 v[148:149], v[108:109], v[148:149]
	v_cvt_pk_bf16_f32 v136, v136, v137
	v_cvt_pk_bf16_f32 v137, v138, v139
	s_nop 0
	v_cvt_pk_bf16_f32 v138, v148, v149
	v_cvt_pk_bf16_f32 v139, v150, v151
	global_store_dwordx4 v[144:145], v[136:139], off
	s_nop 1
	v_or_b32_e32 v144, 48, v2
	v_ashrrev_i32_e32 v145, 31, v144
	v_lshlrev_b64 v[144:145], 10, v[144:145]
	v_lshl_add_u64 v[144:145], v[144:145], 0, v[168:169]
	v_lshl_add_u64 v[146:147], s[16:17], 0, v[134:135]
	v_lshlrev_b64 v[134:135], 1, v[144:145]
	v_lshl_add_u64 v[144:145], s[6:7], 0, v[134:135]
	s_waitcnt vmcnt(15)
; __device__ __forceinline__ float bf_lo(unsigned w) { return __uint_as_float(w << 16); }
; __device__ __forceinline__ float bf_hi(unsigned w) { return __uint_as_float(w & 0xffff0000u); }
; __device__ __forceinline__ float sigm(float x) { return __builtin_amdgcn_rcpf(1.0f + __builtin_amdgcn_exp2f(-1.4426950408889634f * x)); }
; __device__ __forceinline__ u32x4 pack8(f32x4 a, f32x4 b) { u32x4 w; w.x = cvt_pk_bf16(a[0], a[1]); w.y = cvt_pk_bf16(a[2], a[3]); w.z = cvt_pk_bf16(b[0], b[1]); w.w = cvt_pk_bf16(b[2], b[3]); return w; }
;     __device__ __forceinline__ void operator()(const f32x4 (&acc)[2][2][4][2], const Unit& u, int wr, int wc, int fr, int fq) const {
;     ...
;                 for (int bj = 0; bj < 2; ++bj) { const size_t o = ro + bj * HALF; const u32x4 b = *(const u32x4*)(GBr + o);
;                     f32x4 s0, s1; s0[0] = sigm(fmaxf(bf_lo(b.x), -30.f)); s0[1] = sigm(fmaxf(bf_hi(b.x), -30.f)); s0[2] = sigm(fmaxf(bf_lo(b.y), -30.f)); s0[3] = sigm(fmaxf(bf_hi(b.y), -30.f));
;                     s1[0] = sigm(fmaxf(bf_lo(b.z), -30.f)); s1[1] = sigm(fmaxf(bf_hi(b.z), -30.f)); s1[2] = sigm(fmaxf(bf_lo(b.w), -30.f)); s1[3] = sigm(fmaxf(bf_hi(b.w), -30.f));
;                     *(u32x4*)(Mx + o) = pack8(s0 * acc[ai][bj][m][0], s1 * acc[ai][bj][m][1]); } }
	v_lshlrev_b32_e32 v1, 16, v204
	v_and_b32_e32 v136, 0xffff0000, v204
	v_lshlrev_b32_e32 v141, 16, v205
	v_and_b32_e32 v137, 0xffff0000, v205
	v_lshlrev_b32_e32 v148, 16, v206
	v_and_b32_e32 v138, 0xffff0000, v206
	v_lshlrev_b32_e32 v149, 16, v207
	v_and_b32_e32 v139, 0xffff0000, v207
	v_max_f32_e32 v1, v1, v1
	v_max_f32_e32 v136, v136, v136
	v_max_f32_e32 v141, v141, v141
	v_max_f32_e32 v137, v137, v137
	v_max_f32_e32 v148, v148, v148
	v_max_f32_e32 v138, v138, v138
	v_max_f32_e32 v149, v149, v149
	v_max_f32_e32 v139, v139, v139
	v_max_f32_e32 v1, 0xc1f00000, v1
	v_max_f32_e32 v136, 0xc1f00000, v136
	v_max_f32_e32 v141, 0xc1f00000, v141
	v_max_f32_e32 v137, 0xc1f00000, v137
	v_max_f32_e32 v148, 0xc1f00000, v148
	v_max_f32_e32 v138, 0xc1f00000, v138
	v_max_f32_e32 v149, 0xc1f00000, v149
	v_max_f32_e32 v139, 0xc1f00000, v139
	v_mul_f32_e32 v1, 0xbfb8aa3b, v1
	v_mul_f32_e32 v136, 0xbfb8aa3b, v136
	v_mul_f32_e32 v141, 0xbfb8aa3b, v141
	v_mul_f32_e32 v137, 0xbfb8aa3b, v137
	v_mul_f32_e32 v148, 0xbfb8aa3b, v148
	v_mul_f32_e32 v138, 0xbfb8aa3b, v138
	v_mul_f32_e32 v149, 0xbfb8aa3b, v149
	v_mul_f32_e32 v139, 0xbfb8aa3b, v139
	v_exp_f32_e32 v1, v1
	v_exp_f32_e32 v136, v136
	v_exp_f32_e32 v141, v141
	v_exp_f32_e32 v137, v137
	v_exp_f32_e32 v148, v148
	v_exp_f32_e32 v138, v138
	v_exp_f32_e32 v149, v149
	v_exp_f32_e32 v139, v139
	v_add_f32_e32 v1, 1.0, v1
	v_add_f32_e32 v150, 1.0, v136
	v_add_f32_e32 v141, 1.0, v141
	v_add_f32_e32 v151, 1.0, v137
	v_add_f32_e32 v148, 1.0, v148
	v_add_f32_e32 v174, 1.0, v138
	v_add_f32_e32 v149, 1.0, v149
	v_add_f32_e32 v175, 1.0, v139
	v_rcp_f32_e32 v136, v1
	v_rcp_f32_e32 v137, v150
	v_rcp_f32_e32 v138, v141
	v_rcp_f32_e32 v139, v151
	v_rcp_f32_e32 v148, v148
	v_rcp_f32_e32 v150, v149
	v_rcp_f32_e32 v151, v175
	v_rcp_f32_e32 v149, v174
	v_pk_mul_f32 v[138:139], v[82:83], v[138:139]
	v_pk_mul_f32 v[136:137], v[80:81], v[136:137]
	v_pk_mul_f32 v[150:151], v[78:79], v[150:151]
	v_pk_mul_f32 v[148:149], v[76:77], v[148:149]
	v_cvt_pk_bf16_f32 v136, v136, v137
	v_cvt_pk_bf16_f32 v137, v138, v139
	s_nop 0
	v_cvt_pk_bf16_f32 v138, v148, v149
	v_cvt_pk_bf16_f32 v139, v150, v151
	global_store_dwordx4 v[146:147], v[136:139], off
	s_nop 1
	v_lshl_add_u64 v[144:145], s[16:17], 0, v[134:135]
	v_or_b32_e32 v134, 0x100, v134
	v_lshl_add_u64 v[146:147], s[6:7], 0, v[134:135]
	s_waitcnt vmcnt(15)
	v_lshlrev_b32_e32 v1, 16, v208
	v_and_b32_e32 v136, 0xffff0000, v208
	v_lshlrev_b32_e32 v141, 16, v209
	v_and_b32_e32 v137, 0xffff0000, v209
	v_lshlrev_b32_e32 v148, 16, v210
	v_and_b32_e32 v138, 0xffff0000, v210
	v_lshlrev_b32_e32 v149, 16, v211
	v_and_b32_e32 v139, 0xffff0000, v211
	v_max_f32_e32 v1, v1, v1
	v_max_f32_e32 v136, v136, v136
	v_max_f32_e32 v141, v141, v141
	v_max_f32_e32 v137, v137, v137
	v_max_f32_e32 v148, v148, v148
	v_max_f32_e32 v138, v138, v138
	v_max_f32_e32 v149, v149, v149
	v_max_f32_e32 v139, v139, v139
	v_max_f32_e32 v1, 0xc1f00000, v1
	v_max_f32_e32 v136, 0xc1f00000, v136
	v_max_f32_e32 v141, 0xc1f00000, v141
	v_max_f32_e32 v137, 0xc1f00000, v137
	v_max_f32_e32 v148, 0xc1f00000, v148
	v_max_f32_e32 v138, 0xc1f00000, v138
	v_max_f32_e32 v149, 0xc1f00000, v149
	v_max_f32_e32 v139, 0xc1f00000, v139
	v_mul_f32_e32 v1, 0xbfb8aa3b, v1
	v_mul_f32_e32 v136, 0xbfb8aa3b, v136
	v_mul_f32_e32 v141, 0xbfb8aa3b, v141
	v_mul_f32_e32 v137, 0xbfb8aa3b, v137
	v_mul_f32_e32 v148, 0xbfb8aa3b, v148
	v_mul_f32_e32 v138, 0xbfb8aa3b, v138
	v_mul_f32_e32 v149, 0xbfb8aa3b, v149
	v_mul_f32_e32 v139, 0xbfb8aa3b, v139
	v_exp_f32_e32 v1, v1
	v_exp_f32_e32 v136, v136
	v_exp_f32_e32 v141, v141
	v_exp_f32_e32 v137, v137
	v_exp_f32_e32 v148, v148
	v_exp_f32_e32 v138, v138
	v_exp_f32_e32 v149, v149
	v_exp_f32_e32 v139, v139
	v_add_f32_e32 v1, 1.0, v1
	v_add_f32_e32 v150, 1.0, v136
	v_add_f32_e32 v141, 1.0, v141
	v_add_f32_e32 v151, 1.0, v137
	v_add_f32_e32 v148, 1.0, v148
	v_add_f32_e32 v174, 1.0, v138
	v_add_f32_e32 v149, 1.0, v149
	v_add_f32_e32 v175, 1.0, v139
	v_rcp_f32_e32 v136, v1
	v_rcp_f32_e32 v137, v150
	v_rcp_f32_e32 v138, v141
	v_rcp_f32_e32 v139, v151
	v_rcp_f32_e32 v148, v148
	v_rcp_f32_e32 v150, v149
	v_rcp_f32_e32 v151, v175
	v_rcp_f32_e32 v149, v174
	v_pk_mul_f32 v[138:139], v[106:107], v[138:139]
	v_pk_mul_f32 v[136:137], v[104:105], v[136:137]
	v_pk_mul_f32 v[150:151], v[102:103], v[150:151]
	v_pk_mul_f32 v[148:149], v[100:101], v[148:149]
	v_cvt_pk_bf16_f32 v136, v136, v137
	v_cvt_pk_bf16_f32 v137, v138, v139
	s_nop 0
	v_cvt_pk_bf16_f32 v138, v148, v149
	v_cvt_pk_bf16_f32 v139, v150, v151
	global_store_dwordx4 v[144:145], v[136:139], off
	s_nop 1
	v_lshl_add_u64 v[148:149], s[16:17], 0, v[134:135]
	v_lshl_add_u64 v[144:145], v[142:143], 0, s[18:19]
	v_lshl_add_u64 v[146:147], s[6:7], 0, v[144:145]
	v_lshl_add_u64 v[144:145], s[16:17], 0, v[144:145]
	s_waitcnt vmcnt(15)
; __device__ __forceinline__ float bf_lo(unsigned w) { return __uint_as_float(w << 16); }
; __device__ __forceinline__ float bf_hi(unsigned w) { return __uint_as_float(w & 0xffff0000u); }
; __device__ __forceinline__ float sigm(float x) { return __builtin_amdgcn_rcpf(1.0f + __builtin_amdgcn_exp2f(-1.4426950408889634f * x)); }
; __device__ __forceinline__ u32x4 pack8(f32x4 a, f32x4 b) { u32x4 w; w.x = cvt_pk_bf16(a[0], a[1]); w.y = cvt_pk_bf16(a[2], a[3]); w.z = cvt_pk_bf16(b[0], b[1]); w.w = cvt_pk_bf16(b[2], b[3]); return w; }
;     __device__ __forceinline__ void operator()(const f32x4 (&acc)[2][2][4][2], const Unit& u, int wr, int wc, int fr, int fq) const {
;     ...
;                 for (int bj = 0; bj < 2; ++bj) { const size_t o = ro + bj * HALF; const u32x4 b = *(const u32x4*)(GBr + o);
;                     f32x4 s0, s1; s0[0] = sigm(fmaxf(bf_lo(b.x), -30.f)); s0[1] = sigm(fmaxf(bf_hi(b.x), -30.f)); s0[2] = sigm(fmaxf(bf_lo(b.y), -30.f)); s0[3] = sigm(fmaxf(bf_hi(b.y), -30.f));
;                     s1[0] = sigm(fmaxf(bf_lo(b.z), -30.f)); s1[1] = sigm(fmaxf(bf_hi(b.z), -30.f)); s1[2] = sigm(fmaxf(bf_lo(b.w), -30.f)); s1[3] = sigm(fmaxf(bf_hi(b.w), -30.f));
;                     *(u32x4*)(Mx + o) = pack8(s0 * acc[ai][bj][m][0], s1 * acc[ai][bj][m][1]); } }
	v_lshlrev_b32_e32 v1, 16, v212
	v_and_b32_e32 v134, 0xffff0000, v212
	v_lshlrev_b32_e32 v135, 16, v213
	v_and_b32_e32 v136, 0xffff0000, v213
	v_lshlrev_b32_e32 v137, 16, v214
	v_and_b32_e32 v138, 0xffff0000, v214
	v_lshlrev_b32_e32 v141, 16, v215
	v_and_b32_e32 v139, 0xffff0000, v215
	v_max_f32_e32 v1, v1, v1
	v_max_f32_e32 v134, v134, v134
	v_max_f32_e32 v135, v135, v135
	v_max_f32_e32 v136, v136, v136
	v_max_f32_e32 v137, v137, v137
	v_max_f32_e32 v138, v138, v138
	v_max_f32_e32 v141, v141, v141
	v_max_f32_e32 v139, v139, v139
	v_max_f32_e32 v1, 0xc1f00000, v1
	v_max_f32_e32 v134, 0xc1f00000, v134
	v_max_f32_e32 v135, 0xc1f00000, v135
	v_max_f32_e32 v136, 0xc1f00000, v136
	v_max_f32_e32 v137, 0xc1f00000, v137
	v_max_f32_e32 v138, 0xc1f00000, v138
	v_max_f32_e32 v141, 0xc1f00000, v141
	v_max_f32_e32 v139, 0xc1f00000, v139
	v_mul_f32_e32 v1, 0xbfb8aa3b, v1
	v_mul_f32_e32 v134, 0xbfb8aa3b, v134
	v_mul_f32_e32 v135, 0xbfb8aa3b, v135
	v_mul_f32_e32 v136, 0xbfb8aa3b, v136
	v_mul_f32_e32 v137, 0xbfb8aa3b, v137
	v_mul_f32_e32 v138, 0xbfb8aa3b, v138
	v_mul_f32_e32 v141, 0xbfb8aa3b, v141
	v_mul_f32_e32 v139, 0xbfb8aa3b, v139
	v_exp_f32_e32 v1, v1
	v_exp_f32_e32 v134, v134
	v_exp_f32_e32 v135, v135
	v_exp_f32_e32 v136, v136
	v_exp_f32_e32 v137, v137
	v_exp_f32_e32 v138, v138
	v_exp_f32_e32 v141, v141
	v_exp_f32_e32 v139, v139
	v_add_f32_e32 v1, 1.0, v1
	v_add_f32_e32 v150, 1.0, v134
	v_add_f32_e32 v151, 1.0, v135
	v_add_f32_e32 v174, 1.0, v136
	v_add_f32_e32 v175, 1.0, v137
	v_add_f32_e32 v176, 1.0, v138
	v_add_f32_e32 v141, 1.0, v141
	v_add_f32_e32 v139, 1.0, v139
	v_rcp_f32_e32 v134, v1
	v_rcp_f32_e32 v135, v150
	v_rcp_f32_e32 v136, v151
	v_rcp_f32_e32 v137, v174
	v_rcp_f32_e32 v138, v175
	v_rcp_f32_e32 v150, v141
	v_rcp_f32_e32 v151, v139
	v_rcp_f32_e32 v139, v176
	v_pk_mul_f32 v[136:137], v[74:75], v[136:137]
	v_pk_mul_f32 v[134:135], v[72:73], v[134:135]
	v_pk_mul_f32 v[150:151], v[70:71], v[150:151]
	v_pk_mul_f32 v[138:139], v[68:69], v[138:139]
	v_cvt_pk_bf16_f32 v134, v134, v135
	v_cvt_pk_bf16_f32 v135, v136, v137
	s_nop 0
	v_cvt_pk_bf16_f32 v136, v138, v139
	v_cvt_pk_bf16_f32 v137, v150, v151
	global_store_dwordx4 v[148:149], v[134:137], off
	s_nop 1
	v_lshl_add_u64 v[138:139], v[142:143], 0, s[30:31]
	v_lshl_add_u64 v[146:147], s[6:7], 0, v[138:139]
	v_lshl_add_u64 v[138:139], s[16:17], 0, v[138:139]
	s_waitcnt vmcnt(15)
	v_lshlrev_b32_e32 v1, 16, v216
	v_and_b32_e32 v134, 0xffff0000, v216
	v_lshlrev_b32_e32 v141, 16, v217
	v_and_b32_e32 v135, 0xffff0000, v217
	v_lshlrev_b32_e32 v148, 16, v218
	v_and_b32_e32 v136, 0xffff0000, v218
	v_lshlrev_b32_e32 v149, 16, v219
	v_and_b32_e32 v137, 0xffff0000, v219
	v_max_f32_e32 v1, v1, v1
	v_max_f32_e32 v134, v134, v134
	v_max_f32_e32 v141, v141, v141
	v_max_f32_e32 v135, v135, v135
	v_max_f32_e32 v148, v148, v148
	v_max_f32_e32 v136, v136, v136
	v_max_f32_e32 v149, v149, v149
	v_max_f32_e32 v137, v137, v137
	v_max_f32_e32 v1, 0xc1f00000, v1
	v_max_f32_e32 v134, 0xc1f00000, v134
	v_max_f32_e32 v141, 0xc1f00000, v141
	v_max_f32_e32 v135, 0xc1f00000, v135
	v_max_f32_e32 v148, 0xc1f00000, v148
	v_max_f32_e32 v136, 0xc1f00000, v136
	v_max_f32_e32 v149, 0xc1f00000, v149
	v_max_f32_e32 v137, 0xc1f00000, v137
	v_mul_f32_e32 v1, 0xbfb8aa3b, v1
	v_mul_f32_e32 v134, 0xbfb8aa3b, v134
	v_mul_f32_e32 v141, 0xbfb8aa3b, v141
	v_mul_f32_e32 v135, 0xbfb8aa3b, v135
	v_mul_f32_e32 v148, 0xbfb8aa3b, v148
	v_mul_f32_e32 v136, 0xbfb8aa3b, v136
	v_mul_f32_e32 v149, 0xbfb8aa3b, v149
	v_mul_f32_e32 v137, 0xbfb8aa3b, v137
	v_exp_f32_e32 v1, v1
	v_exp_f32_e32 v134, v134
	v_exp_f32_e32 v141, v141
	v_exp_f32_e32 v135, v135
	v_exp_f32_e32 v148, v148
	v_exp_f32_e32 v136, v136
	v_exp_f32_e32 v149, v149
	v_exp_f32_e32 v137, v137
	v_add_f32_e32 v1, 1.0, v1
	v_add_f32_e32 v150, 1.0, v134
	v_add_f32_e32 v141, 1.0, v141
	v_add_f32_e32 v151, 1.0, v135
	v_add_f32_e32 v148, 1.0, v148
	v_add_f32_e32 v174, 1.0, v136
	v_add_f32_e32 v149, 1.0, v149
	v_add_f32_e32 v175, 1.0, v137
	v_rcp_f32_e32 v134, v1
	v_rcp_f32_e32 v135, v150
	v_rcp_f32_e32 v136, v141
	v_rcp_f32_e32 v137, v151
	v_rcp_f32_e32 v148, v148
	v_rcp_f32_e32 v150, v149
	v_rcp_f32_e32 v151, v175
	v_rcp_f32_e32 v149, v174
	v_pk_mul_f32 v[136:137], v[66:67], v[136:137]
	v_pk_mul_f32 v[134:135], v[64:65], v[134:135]
	v_pk_mul_f32 v[150:151], v[62:63], v[150:151]
	v_pk_mul_f32 v[148:149], v[60:61], v[148:149]
	v_cvt_pk_bf16_f32 v134, v134, v135
	v_cvt_pk_bf16_f32 v135, v136, v137
	s_nop 0
	v_cvt_pk_bf16_f32 v136, v148, v149
	v_cvt_pk_bf16_f32 v137, v150, v151
	global_store_dwordx4 v[144:145], v[134:137], off
	s_nop 1
	v_lshl_add_u64 v[144:145], v[142:143], 0, s[34:35]
	v_lshl_add_u64 v[146:147], s[6:7], 0, v[144:145]
	v_lshl_add_u64 v[144:145], s[16:17], 0, v[144:145]
	s_waitcnt vmcnt(15)
; __device__ __forceinline__ float bf_lo(unsigned w) { return __uint_as_float(w << 16); }
; __device__ __forceinline__ float bf_hi(unsigned w) { return __uint_as_float(w & 0xffff0000u); }
; __device__ __forceinline__ float sigm(float x) { return __builtin_amdgcn_rcpf(1.0f + __builtin_amdgcn_exp2f(-1.4426950408889634f * x)); }
; __device__ __forceinline__ u32x4 pack8(f32x4 a, f32x4 b) { u32x4 w; w.x = cvt_pk_bf16(a[0], a[1]); w.y = cvt_pk_bf16(a[2], a[3]); w.z = cvt_pk_bf16(b[0], b[1]); w.w = cvt_pk_bf16(b[2], b[3]); return w; }
;     __device__ __forceinline__ void operator()(const f32x4 (&acc)[2][2][4][2], const Unit& u, int wr, int wc, int fr, int fq) const {
;     ...
;                 for (int bj = 0; bj < 2; ++bj) { const size_t o = ro + bj * HALF; const u32x4 b = *(const u32x4*)(GBr + o);
;                     f32x4 s0, s1; s0[0] = sigm(fmaxf(bf_lo(b.x), -30.f)); s0[1] = sigm(fmaxf(bf_hi(b.x), -30.f)); s0[2] = sigm(fmaxf(bf_lo(b.y), -30.f)); s0[3] = sigm(fmaxf(bf_hi(b.y), -30.f));
;                     s1[0] = sigm(fmaxf(bf_lo(b.z), -30.f)); s1[1] = sigm(fmaxf(bf_hi(b.z), -30.f)); s1[2] = sigm(fmaxf(bf_lo(b.w), -30.f)); s1[3] = sigm(fmaxf(bf_hi(b.w), -30.f));
;                     *(u32x4*)(Mx + o) = pack8(s0 * acc[ai][bj][m][0], s1 * acc[ai][bj][m][1]); } }
	v_lshlrev_b32_e32 v1, 16, v220
	v_and_b32_e32 v134, 0xffff0000, v220
	v_lshlrev_b32_e32 v141, 16, v221
	v_and_b32_e32 v135, 0xffff0000, v221
	v_lshlrev_b32_e32 v148, 16, v222
	v_and_b32_e32 v136, 0xffff0000, v222
	v_lshlrev_b32_e32 v149, 16, v223
	v_and_b32_e32 v137, 0xffff0000, v223
	v_max_f32_e32 v1, v1, v1
	v_max_f32_e32 v134, v134, v134
	v_max_f32_e32 v141, v141, v141
	v_max_f32_e32 v135, v135, v135
	v_max_f32_e32 v148, v148, v148
	v_max_f32_e32 v136, v136, v136
	v_max_f32_e32 v149, v149, v149
	v_max_f32_e32 v137, v137, v137
	v_max_f32_e32 v1, 0xc1f00000, v1
	v_max_f32_e32 v134, 0xc1f00000, v134
	v_max_f32_e32 v141, 0xc1f00000, v141
	v_max_f32_e32 v135, 0xc1f00000, v135
	v_max_f32_e32 v148, 0xc1f00000, v148
	v_max_f32_e32 v136, 0xc1f00000, v136
	v_max_f32_e32 v149, 0xc1f00000, v149
	v_max_f32_e32 v137, 0xc1f00000, v137
	v_mul_f32_e32 v1, 0xbfb8aa3b, v1
	v_mul_f32_e32 v134, 0xbfb8aa3b, v134
	v_mul_f32_e32 v141, 0xbfb8aa3b, v141
	v_mul_f32_e32 v135, 0xbfb8aa3b, v135
	v_mul_f32_e32 v148, 0xbfb8aa3b, v148
	v_mul_f32_e32 v136, 0xbfb8aa3b, v136
	v_mul_f32_e32 v149, 0xbfb8aa3b, v149
	v_mul_f32_e32 v137, 0xbfb8aa3b, v137
	v_exp_f32_e32 v1, v1
	v_exp_f32_e32 v134, v134
	v_exp_f32_e32 v141, v141
	v_exp_f32_e32 v135, v135
	v_exp_f32_e32 v148, v148
	v_exp_f32_e32 v136, v136
	v_exp_f32_e32 v149, v149
	v_exp_f32_e32 v137, v137
	v_add_f32_e32 v1, 1.0, v1
	v_add_f32_e32 v150, 1.0, v134
	v_add_f32_e32 v141, 1.0, v141
	v_add_f32_e32 v151, 1.0, v135
	v_add_f32_e32 v148, 1.0, v148
	v_add_f32_e32 v174, 1.0, v136
	v_add_f32_e32 v149, 1.0, v149
	v_add_f32_e32 v175, 1.0, v137
	v_rcp_f32_e32 v134, v1
	v_rcp_f32_e32 v135, v150
	v_rcp_f32_e32 v136, v141
	v_rcp_f32_e32 v137, v151
	v_rcp_f32_e32 v148, v148
	v_rcp_f32_e32 v150, v149
	v_rcp_f32_e32 v151, v175
	v_rcp_f32_e32 v149, v174
	v_pk_mul_f32 v[136:137], v[34:35], v[136:137]
	v_pk_mul_f32 v[134:135], v[32:33], v[134:135]
	v_pk_mul_f32 v[150:151], v[30:31], v[150:151]
	v_pk_mul_f32 v[148:149], v[28:29], v[148:149]
	v_cvt_pk_bf16_f32 v134, v134, v135
	v_cvt_pk_bf16_f32 v135, v136, v137
	s_nop 0
	v_cvt_pk_bf16_f32 v136, v148, v149
	v_cvt_pk_bf16_f32 v137, v150, v151
	global_store_dwordx4 v[138:139], v[134:137], off
	s_nop 1
	v_lshl_add_u64 v[138:139], v[142:143], 0, s[36:37]
	v_lshl_add_u64 v[146:147], s[6:7], 0, v[138:139]
	v_lshl_add_u64 v[138:139], s[16:17], 0, v[138:139]
	s_waitcnt vmcnt(15)
	v_lshlrev_b32_e32 v1, 16, v224
	v_and_b32_e32 v134, 0xffff0000, v224
	v_lshlrev_b32_e32 v141, 16, v225
	v_and_b32_e32 v135, 0xffff0000, v225
	v_lshlrev_b32_e32 v148, 16, v226
	v_and_b32_e32 v136, 0xffff0000, v226
	v_lshlrev_b32_e32 v149, 16, v227
	v_and_b32_e32 v137, 0xffff0000, v227
	v_max_f32_e32 v1, v1, v1
	v_max_f32_e32 v134, v134, v134
	v_max_f32_e32 v141, v141, v141
	v_max_f32_e32 v135, v135, v135
	v_max_f32_e32 v148, v148, v148
	v_max_f32_e32 v136, v136, v136
	v_max_f32_e32 v149, v149, v149
	v_max_f32_e32 v137, v137, v137
	v_max_f32_e32 v1, 0xc1f00000, v1
	v_max_f32_e32 v134, 0xc1f00000, v134
	v_max_f32_e32 v141, 0xc1f00000, v141
	v_max_f32_e32 v135, 0xc1f00000, v135
	v_max_f32_e32 v148, 0xc1f00000, v148
	v_max_f32_e32 v136, 0xc1f00000, v136
	v_max_f32_e32 v149, 0xc1f00000, v149
	v_max_f32_e32 v137, 0xc1f00000, v137
	v_mul_f32_e32 v1, 0xbfb8aa3b, v1
	v_mul_f32_e32 v134, 0xbfb8aa3b, v134
	v_mul_f32_e32 v141, 0xbfb8aa3b, v141
	v_mul_f32_e32 v135, 0xbfb8aa3b, v135
	v_mul_f32_e32 v148, 0xbfb8aa3b, v148
	v_mul_f32_e32 v136, 0xbfb8aa3b, v136
	v_mul_f32_e32 v149, 0xbfb8aa3b, v149
	v_mul_f32_e32 v137, 0xbfb8aa3b, v137
	v_exp_f32_e32 v1, v1
	v_exp_f32_e32 v134, v134
	v_exp_f32_e32 v141, v141
	v_exp_f32_e32 v135, v135
	v_exp_f32_e32 v148, v148
	v_exp_f32_e32 v136, v136
	v_exp_f32_e32 v149, v149
	v_exp_f32_e32 v137, v137
	v_add_f32_e32 v1, 1.0, v1
	v_add_f32_e32 v150, 1.0, v134
	v_add_f32_e32 v141, 1.0, v141
	v_add_f32_e32 v151, 1.0, v135
	v_add_f32_e32 v148, 1.0, v148
	v_add_f32_e32 v174, 1.0, v136
	v_add_f32_e32 v149, 1.0, v149
	v_add_f32_e32 v175, 1.0, v137
	v_rcp_f32_e32 v134, v1
	v_rcp_f32_e32 v135, v150
	v_rcp_f32_e32 v136, v141
	v_rcp_f32_e32 v137, v151
	v_rcp_f32_e32 v148, v148
	v_rcp_f32_e32 v150, v149
	v_rcp_f32_e32 v151, v175
	v_rcp_f32_e32 v149, v174
	v_pk_mul_f32 v[136:137], v[58:59], v[136:137]
	v_pk_mul_f32 v[134:135], v[56:57], v[134:135]
	v_pk_mul_f32 v[150:151], v[54:55], v[150:151]
	v_pk_mul_f32 v[148:149], v[52:53], v[148:149]
	v_cvt_pk_bf16_f32 v134, v134, v135
	v_cvt_pk_bf16_f32 v135, v136, v137
	s_nop 0
	v_cvt_pk_bf16_f32 v136, v148, v149
	v_cvt_pk_bf16_f32 v137, v150, v151
	global_store_dwordx4 v[144:145], v[134:137], off
	s_nop 1
	v_lshl_add_u64 v[144:145], v[142:143], 0, s[38:39]
	v_lshl_add_u64 v[146:147], s[6:7], 0, v[144:145]
	v_lshl_add_u64 v[144:145], s[16:17], 0, v[144:145]
	s_waitcnt vmcnt(15)
; __device__ __forceinline__ float bf_lo(unsigned w) { return __uint_as_float(w << 16); }
; __device__ __forceinline__ float bf_hi(unsigned w) { return __uint_as_float(w & 0xffff0000u); }
; __device__ __forceinline__ float sigm(float x) { return __builtin_amdgcn_rcpf(1.0f + __builtin_amdgcn_exp2f(-1.4426950408889634f * x)); }
; __device__ __forceinline__ u32x4 pack8(f32x4 a, f32x4 b) { u32x4 w; w.x = cvt_pk_bf16(a[0], a[1]); w.y = cvt_pk_bf16(a[2], a[3]); w.z = cvt_pk_bf16(b[0], b[1]); w.w = cvt_pk_bf16(b[2], b[3]); return w; }
;     __device__ __forceinline__ void operator()(const f32x4 (&acc)[2][2][4][2], const Unit& u, int wr, int wc, int fr, int fq) const {
;     ...
;                 for (int bj = 0; bj < 2; ++bj) { const size_t o = ro + bj * HALF; const u32x4 b = *(const u32x4*)(GBr + o);
;                     f32x4 s0, s1; s0[0] = sigm(fmaxf(bf_lo(b.x), -30.f)); s0[1] = sigm(fmaxf(bf_hi(b.x), -30.f)); s0[2] = sigm(fmaxf(bf_lo(b.y), -30.f)); s0[3] = sigm(fmaxf(bf_hi(b.y), -30.f));
;                     s1[0] = sigm(fmaxf(bf_lo(b.z), -30.f)); s1[1] = sigm(fmaxf(bf_hi(b.z), -30.f)); s1[2] = sigm(fmaxf(bf_lo(b.w), -30.f)); s1[3] = sigm(fmaxf(bf_hi(b.w), -30.f));
;                     *(u32x4*)(Mx + o) = pack8(s0 * acc[ai][bj][m][0], s1 * acc[ai][bj][m][1]); } }
	v_lshlrev_b32_e32 v1, 16, v238
	v_and_b32_e32 v134, 0xffff0000, v238
	v_lshlrev_b32_e32 v141, 16, v239
	v_and_b32_e32 v135, 0xffff0000, v239
	v_lshlrev_b32_e32 v148, 16, v240
	v_and_b32_e32 v136, 0xffff0000, v240
	v_lshlrev_b32_e32 v149, 16, v241
	v_and_b32_e32 v137, 0xffff0000, v241
	v_max_f32_e32 v1, v1, v1
	v_max_f32_e32 v134, v134, v134
	v_max_f32_e32 v141, v141, v141
	v_max_f32_e32 v135, v135, v135
	v_max_f32_e32 v148, v148, v148
	v_max_f32_e32 v136, v136, v136
	v_max_f32_e32 v149, v149, v149
	v_max_f32_e32 v137, v137, v137
	v_max_f32_e32 v1, 0xc1f00000, v1
	v_max_f32_e32 v134, 0xc1f00000, v134
	v_max_f32_e32 v141, 0xc1f00000, v141
	v_max_f32_e32 v135, 0xc1f00000, v135
	v_max_f32_e32 v148, 0xc1f00000, v148
	v_max_f32_e32 v136, 0xc1f00000, v136
	v_max_f32_e32 v149, 0xc1f00000, v149
	v_max_f32_e32 v137, 0xc1f00000, v137
	v_mul_f32_e32 v1, 0xbfb8aa3b, v1
	v_mul_f32_e32 v134, 0xbfb8aa3b, v134
	v_mul_f32_e32 v141, 0xbfb8aa3b, v141
	v_mul_f32_e32 v135, 0xbfb8aa3b, v135
	v_mul_f32_e32 v148, 0xbfb8aa3b, v148
	v_mul_f32_e32 v136, 0xbfb8aa3b, v136
	v_mul_f32_e32 v149, 0xbfb8aa3b, v149
	v_mul_f32_e32 v137, 0xbfb8aa3b, v137
	v_exp_f32_e32 v1, v1
	v_exp_f32_e32 v134, v134
	v_exp_f32_e32 v141, v141
	v_exp_f32_e32 v135, v135
	v_exp_f32_e32 v148, v148
	v_exp_f32_e32 v136, v136
	v_exp_f32_e32 v149, v149
	v_exp_f32_e32 v137, v137
	v_add_f32_e32 v1, 1.0, v1
	v_add_f32_e32 v150, 1.0, v134
	v_add_f32_e32 v141, 1.0, v141
	v_add_f32_e32 v151, 1.0, v135
	v_add_f32_e32 v148, 1.0, v148
	v_add_f32_e32 v174, 1.0, v136
	v_add_f32_e32 v149, 1.0, v149
	v_add_f32_e32 v175, 1.0, v137
	v_rcp_f32_e32 v134, v1
	v_rcp_f32_e32 v135, v150
	v_rcp_f32_e32 v136, v141
	v_rcp_f32_e32 v137, v151
	v_rcp_f32_e32 v148, v148
	v_rcp_f32_e32 v150, v149
	v_rcp_f32_e32 v151, v175
	v_rcp_f32_e32 v149, v174
	v_pk_mul_f32 v[136:137], v[26:27], v[136:137]
	v_pk_mul_f32 v[134:135], v[24:25], v[134:135]
	v_pk_mul_f32 v[150:151], v[22:23], v[150:151]
	v_pk_mul_f32 v[148:149], v[20:21], v[148:149]
	v_cvt_pk_bf16_f32 v134, v134, v135
	v_cvt_pk_bf16_f32 v135, v136, v137
	s_nop 0
	v_cvt_pk_bf16_f32 v136, v148, v149
	v_cvt_pk_bf16_f32 v137, v150, v151
	global_store_dwordx4 v[138:139], v[134:137], off
	s_nop 1
	v_lshl_add_u64 v[138:139], v[142:143], 0, s[40:41]
	v_lshl_add_u64 v[146:147], s[6:7], 0, v[138:139]
	v_lshl_add_u64 v[138:139], s[16:17], 0, v[138:139]
	s_waitcnt vmcnt(15)
	v_lshlrev_b32_e32 v1, 16, v242
	v_and_b32_e32 v134, 0xffff0000, v242
	v_lshlrev_b32_e32 v141, 16, v243
	v_and_b32_e32 v135, 0xffff0000, v243
	v_lshlrev_b32_e32 v148, 16, v244
	v_and_b32_e32 v136, 0xffff0000, v244
	v_lshlrev_b32_e32 v149, 16, v245
	v_and_b32_e32 v137, 0xffff0000, v245
	v_max_f32_e32 v1, v1, v1
	v_max_f32_e32 v134, v134, v134
	v_max_f32_e32 v141, v141, v141
	v_max_f32_e32 v135, v135, v135
	v_max_f32_e32 v148, v148, v148
	v_max_f32_e32 v136, v136, v136
	v_max_f32_e32 v149, v149, v149
	v_max_f32_e32 v137, v137, v137
	v_max_f32_e32 v1, 0xc1f00000, v1
	v_max_f32_e32 v134, 0xc1f00000, v134
	v_max_f32_e32 v141, 0xc1f00000, v141
	v_max_f32_e32 v135, 0xc1f00000, v135
	v_max_f32_e32 v148, 0xc1f00000, v148
	v_max_f32_e32 v136, 0xc1f00000, v136
	v_max_f32_e32 v149, 0xc1f00000, v149
	v_max_f32_e32 v137, 0xc1f00000, v137
	v_mul_f32_e32 v1, 0xbfb8aa3b, v1
	v_mul_f32_e32 v134, 0xbfb8aa3b, v134
	v_mul_f32_e32 v141, 0xbfb8aa3b, v141
	v_mul_f32_e32 v135, 0xbfb8aa3b, v135
	v_mul_f32_e32 v148, 0xbfb8aa3b, v148
	v_mul_f32_e32 v136, 0xbfb8aa3b, v136
	v_mul_f32_e32 v149, 0xbfb8aa3b, v149
	v_mul_f32_e32 v137, 0xbfb8aa3b, v137
	v_exp_f32_e32 v1, v1
	v_exp_f32_e32 v134, v134
	v_exp_f32_e32 v141, v141
	v_exp_f32_e32 v135, v135
	v_exp_f32_e32 v148, v148
	v_exp_f32_e32 v136, v136
	v_exp_f32_e32 v149, v149
	v_exp_f32_e32 v137, v137
	v_add_f32_e32 v1, 1.0, v1
	v_add_f32_e32 v150, 1.0, v134
	v_add_f32_e32 v141, 1.0, v141
	v_add_f32_e32 v151, 1.0, v135
	v_add_f32_e32 v148, 1.0, v148
	v_add_f32_e32 v174, 1.0, v136
	v_add_f32_e32 v149, 1.0, v149
	v_add_f32_e32 v175, 1.0, v137
	v_rcp_f32_e32 v134, v1
	v_rcp_f32_e32 v135, v150
	v_rcp_f32_e32 v136, v141
	v_rcp_f32_e32 v137, v151
	v_rcp_f32_e32 v148, v148
	v_rcp_f32_e32 v150, v149
	v_rcp_f32_e32 v151, v175
	v_rcp_f32_e32 v149, v174
	v_pk_mul_f32 v[136:137], v[50:51], v[136:137]
	v_pk_mul_f32 v[134:135], v[48:49], v[134:135]
	v_pk_mul_f32 v[150:151], v[46:47], v[150:151]
	v_pk_mul_f32 v[148:149], v[44:45], v[148:149]
	v_cvt_pk_bf16_f32 v134, v134, v135
	v_cvt_pk_bf16_f32 v135, v136, v137
	s_nop 0
	v_cvt_pk_bf16_f32 v136, v148, v149
	v_cvt_pk_bf16_f32 v137, v150, v151
	global_store_dwordx4 v[144:145], v[134:137], off
	s_nop 1
	v_lshl_add_u64 v[144:145], v[142:143], 0, s[42:43]
	v_lshl_add_u64 v[146:147], s[6:7], 0, v[144:145]
	v_lshl_add_u64 v[144:145], s[16:17], 0, v[144:145]
	s_waitcnt vmcnt(15)
; __device__ __forceinline__ float bf_lo(unsigned w) { return __uint_as_float(w << 16); }
; __device__ __forceinline__ float bf_hi(unsigned w) { return __uint_as_float(w & 0xffff0000u); }
; __device__ __forceinline__ float sigm(float x) { return __builtin_amdgcn_rcpf(1.0f + __builtin_amdgcn_exp2f(-1.4426950408889634f * x)); }
; __device__ __forceinline__ u32x4 pack8(f32x4 a, f32x4 b) { u32x4 w; w.x = cvt_pk_bf16(a[0], a[1]); w.y = cvt_pk_bf16(a[2], a[3]); w.z = cvt_pk_bf16(b[0], b[1]); w.w = cvt_pk_bf16(b[2], b[3]); return w; }
;     __device__ __forceinline__ void operator()(const f32x4 (&acc)[2][2][4][2], const Unit& u, int wr, int wc, int fr, int fq) const {
;     ...
;                 for (int bj = 0; bj < 2; ++bj) { const size_t o = ro + bj * HALF; const u32x4 b = *(const u32x4*)(GBr + o);
;                     f32x4 s0, s1; s0[0] = sigm(fmaxf(bf_lo(b.x), -30.f)); s0[1] = sigm(fmaxf(bf_hi(b.x), -30.f)); s0[2] = sigm(fmaxf(bf_lo(b.y), -30.f)); s0[3] = sigm(fmaxf(bf_hi(b.y), -30.f));
;                     s1[0] = sigm(fmaxf(bf_lo(b.z), -30.f)); s1[1] = sigm(fmaxf(bf_hi(b.z), -30.f)); s1[2] = sigm(fmaxf(bf_lo(b.w), -30.f)); s1[3] = sigm(fmaxf(bf_hi(b.w), -30.f));
;                     *(u32x4*)(Mx + o) = pack8(s0 * acc[ai][bj][m][0], s1 * acc[ai][bj][m][1]); } }
	v_lshlrev_b32_e32 v1, 16, v246
	v_and_b32_e32 v134, 0xffff0000, v246
	v_lshlrev_b32_e32 v141, 16, v247
	v_and_b32_e32 v135, 0xffff0000, v247
	v_lshlrev_b32_e32 v148, 16, v248
	v_and_b32_e32 v136, 0xffff0000, v248
	v_lshlrev_b32_e32 v149, 16, v249
	v_and_b32_e32 v137, 0xffff0000, v249
	v_max_f32_e32 v1, v1, v1
	v_max_f32_e32 v134, v134, v134
	v_max_f32_e32 v141, v141, v141
	v_max_f32_e32 v135, v135, v135
	v_max_f32_e32 v148, v148, v148
	v_max_f32_e32 v136, v136, v136
	v_max_f32_e32 v149, v149, v149
	v_max_f32_e32 v137, v137, v137
	v_max_f32_e32 v1, 0xc1f00000, v1
	v_max_f32_e32 v134, 0xc1f00000, v134
	v_max_f32_e32 v141, 0xc1f00000, v141
	v_max_f32_e32 v135, 0xc1f00000, v135
	v_max_f32_e32 v148, 0xc1f00000, v148
	v_max_f32_e32 v136, 0xc1f00000, v136
	v_max_f32_e32 v149, 0xc1f00000, v149
	v_max_f32_e32 v137, 0xc1f00000, v137
	v_mul_f32_e32 v1, 0xbfb8aa3b, v1
	v_mul_f32_e32 v134, 0xbfb8aa3b, v134
	v_mul_f32_e32 v141, 0xbfb8aa3b, v141
	v_mul_f32_e32 v135, 0xbfb8aa3b, v135
	v_mul_f32_e32 v148, 0xbfb8aa3b, v148
	v_mul_f32_e32 v136, 0xbfb8aa3b, v136
	v_mul_f32_e32 v149, 0xbfb8aa3b, v149
	v_mul_f32_e32 v137, 0xbfb8aa3b, v137
	v_exp_f32_e32 v1, v1
	v_exp_f32_e32 v134, v134
	v_exp_f32_e32 v141, v141
	v_exp_f32_e32 v135, v135
	v_exp_f32_e32 v148, v148
	v_exp_f32_e32 v136, v136
	v_exp_f32_e32 v149, v149
	v_exp_f32_e32 v137, v137
	v_add_f32_e32 v1, 1.0, v1
	v_add_f32_e32 v150, 1.0, v134
	v_add_f32_e32 v141, 1.0, v141
	v_add_f32_e32 v151, 1.0, v135
	v_add_f32_e32 v148, 1.0, v148
	v_add_f32_e32 v174, 1.0, v136
	v_add_f32_e32 v149, 1.0, v149
	v_add_f32_e32 v175, 1.0, v137
	v_rcp_f32_e32 v134, v1
	v_rcp_f32_e32 v135, v150
	v_rcp_f32_e32 v136, v141
	v_rcp_f32_e32 v137, v151
	v_rcp_f32_e32 v148, v148
	v_rcp_f32_e32 v150, v149
	v_rcp_f32_e32 v151, v175
	v_rcp_f32_e32 v149, v174
	v_pk_mul_f32 v[136:137], v[18:19], v[136:137]
	v_pk_mul_f32 v[134:135], v[16:17], v[134:135]
	v_pk_mul_f32 v[150:151], v[14:15], v[150:151]
	v_pk_mul_f32 v[148:149], v[12:13], v[148:149]
	v_cvt_pk_bf16_f32 v134, v134, v135
	v_cvt_pk_bf16_f32 v135, v136, v137
	s_nop 0
	v_cvt_pk_bf16_f32 v136, v148, v149
	v_cvt_pk_bf16_f32 v137, v150, v151
	global_store_dwordx4 v[138:139], v[134:137], off
	s_nop 1
	v_lshl_add_u64 v[138:139], v[142:143], 0, s[44:45]
	v_lshl_add_u64 v[146:147], s[6:7], 0, v[138:139]
	v_lshl_add_u64 v[138:139], s[16:17], 0, v[138:139]
	s_waitcnt vmcnt(15)
	v_lshlrev_b32_e32 v1, 16, v252
	v_and_b32_e32 v134, 0xffff0000, v252
	v_lshlrev_b32_e32 v141, 16, v253
	v_and_b32_e32 v135, 0xffff0000, v253
	v_lshlrev_b32_e32 v148, 16, v254
	v_and_b32_e32 v136, 0xffff0000, v254
	v_lshlrev_b32_e32 v149, 16, v255
	v_and_b32_e32 v137, 0xffff0000, v255
	v_max_f32_e32 v1, v1, v1
	v_max_f32_e32 v134, v134, v134
	v_max_f32_e32 v141, v141, v141
	v_max_f32_e32 v135, v135, v135
	v_max_f32_e32 v148, v148, v148
	v_max_f32_e32 v136, v136, v136
	v_max_f32_e32 v149, v149, v149
	v_max_f32_e32 v137, v137, v137
	v_max_f32_e32 v1, 0xc1f00000, v1
	v_max_f32_e32 v134, 0xc1f00000, v134
	v_max_f32_e32 v141, 0xc1f00000, v141
	v_max_f32_e32 v135, 0xc1f00000, v135
	v_max_f32_e32 v148, 0xc1f00000, v148
	v_max_f32_e32 v136, 0xc1f00000, v136
	v_max_f32_e32 v149, 0xc1f00000, v149
	v_max_f32_e32 v137, 0xc1f00000, v137
	v_mul_f32_e32 v1, 0xbfb8aa3b, v1
	v_mul_f32_e32 v134, 0xbfb8aa3b, v134
	v_mul_f32_e32 v141, 0xbfb8aa3b, v141
	v_mul_f32_e32 v135, 0xbfb8aa3b, v135
	v_mul_f32_e32 v148, 0xbfb8aa3b, v148
	v_mul_f32_e32 v136, 0xbfb8aa3b, v136
	v_mul_f32_e32 v149, 0xbfb8aa3b, v149
	v_mul_f32_e32 v137, 0xbfb8aa3b, v137
	v_exp_f32_e32 v1, v1
	v_exp_f32_e32 v134, v134
	v_exp_f32_e32 v141, v141
	v_exp_f32_e32 v135, v135
	v_exp_f32_e32 v148, v148
	v_exp_f32_e32 v136, v136
	v_exp_f32_e32 v149, v149
	v_exp_f32_e32 v137, v137
	v_add_f32_e32 v1, 1.0, v1
	v_add_f32_e32 v150, 1.0, v134
	v_add_f32_e32 v141, 1.0, v141
	v_add_f32_e32 v151, 1.0, v135
	v_add_f32_e32 v148, 1.0, v148
	v_add_f32_e32 v174, 1.0, v136
	v_add_f32_e32 v149, 1.0, v149
	v_add_f32_e32 v175, 1.0, v137
	v_rcp_f32_e32 v134, v1
	v_rcp_f32_e32 v135, v150
	v_rcp_f32_e32 v136, v141
	v_rcp_f32_e32 v137, v151
	v_rcp_f32_e32 v148, v148
	v_rcp_f32_e32 v150, v149
	v_rcp_f32_e32 v151, v175
	v_rcp_f32_e32 v149, v174
	v_pk_mul_f32 v[136:137], v[42:43], v[136:137]
	v_pk_mul_f32 v[134:135], v[40:41], v[134:135]
	v_pk_mul_f32 v[150:151], v[38:39], v[150:151]
	v_pk_mul_f32 v[148:149], v[36:37], v[148:149]
	v_cvt_pk_bf16_f32 v134, v134, v135
	v_cvt_pk_bf16_f32 v135, v136, v137
	s_nop 0
	v_cvt_pk_bf16_f32 v136, v148, v149
	v_cvt_pk_bf16_f32 v137, v150, v151
	global_store_dwordx4 v[144:145], v[134:137], off
	s_nop 1
	s_waitcnt vmcnt(15)
	v_lshlrev_b32_e32 v1, 16, v184
	v_and_b32_e32 v134, 0xffff0000, v184
	v_lshlrev_b32_e32 v141, 16, v185
	v_and_b32_e32 v135, 0xffff0000, v185
	v_lshlrev_b32_e32 v144, 16, v186
	v_and_b32_e32 v136, 0xffff0000, v186
	v_lshlrev_b32_e32 v145, 16, v187
	v_and_b32_e32 v137, 0xffff0000, v187
	v_max_f32_e32 v1, v1, v1
	v_max_f32_e32 v134, v134, v134
	v_max_f32_e32 v141, v141, v141
	v_max_f32_e32 v135, v135, v135
	v_max_f32_e32 v144, v144, v144
	v_max_f32_e32 v136, v136, v136
	v_max_f32_e32 v145, v145, v145
	v_max_f32_e32 v137, v137, v137
	v_max_f32_e32 v1, 0xc1f00000, v1
	v_max_f32_e32 v134, 0xc1f00000, v134
	v_max_f32_e32 v141, 0xc1f00000, v141
	v_max_f32_e32 v135, 0xc1f00000, v135
	v_max_f32_e32 v144, 0xc1f00000, v144
	v_max_f32_e32 v136, 0xc1f00000, v136
	v_max_f32_e32 v145, 0xc1f00000, v145
	v_max_f32_e32 v137, 0xc1f00000, v137
	v_mul_f32_e32 v1, 0xbfb8aa3b, v1
	v_mul_f32_e32 v134, 0xbfb8aa3b, v134
	v_mul_f32_e32 v141, 0xbfb8aa3b, v141
	v_mul_f32_e32 v135, 0xbfb8aa3b, v135
	v_mul_f32_e32 v144, 0xbfb8aa3b, v144
	v_mul_f32_e32 v136, 0xbfb8aa3b, v136
	v_mul_f32_e32 v145, 0xbfb8aa3b, v145
	v_mul_f32_e32 v137, 0xbfb8aa3b, v137
	v_exp_f32_e32 v1, v1
	v_exp_f32_e32 v134, v134
	v_exp_f32_e32 v141, v141
	v_exp_f32_e32 v135, v135
	v_exp_f32_e32 v144, v144
	v_exp_f32_e32 v136, v136
	v_exp_f32_e32 v145, v145
	v_exp_f32_e32 v137, v137
	v_add_f32_e32 v1, 1.0, v1
	v_add_f32_e32 v146, 1.0, v134
	v_add_f32_e32 v141, 1.0, v141
	v_add_f32_e32 v147, 1.0, v135
	v_add_f32_e32 v144, 1.0, v144
	v_add_f32_e32 v148, 1.0, v136
	v_add_f32_e32 v145, 1.0, v145
	v_add_f32_e32 v149, 1.0, v137
	v_rcp_f32_e32 v134, v1
	v_rcp_f32_e32 v135, v146
	v_rcp_f32_e32 v136, v141
	v_rcp_f32_e32 v137, v147
	v_rcp_f32_e32 v144, v144
	v_rcp_f32_e32 v146, v145
	v_rcp_f32_e32 v147, v149
	v_rcp_f32_e32 v145, v148
	v_pk_mul_f32 v[136:137], v[10:11], v[136:137]
	v_pk_mul_f32 v[134:135], v[8:9], v[134:135]
	v_pk_mul_f32 v[146:147], v[6:7], v[146:147]
	v_pk_mul_f32 v[144:145], v[4:5], v[144:145]
	v_cvt_pk_bf16_f32 v134, v134, v135
	v_cvt_pk_bf16_f32 v135, v136, v137
	s_nop 0
	v_cvt_pk_bf16_f32 v136, v144, v145
	v_cvt_pk_bf16_f32 v137, v146, v147
	global_store_dwordx4 v[138:139], v[134:137], off
	s_cbranch_execnz .LBB0_1035
